# scan wave as chunked recurrence on f32 16x16x4 MFMA (Gram + U + rank-16 update), static LDS +16 KiB
# baseline (speedup 1.0000x reference)
.LBB0_565:
	s_lshl_b32 s0, s22, 2
	v_readlane_b32 s18, v253, 37
	s_add_i32 s3, s20, s0
	v_readlane_b32 s19, v253, 38
	s_and_b64 s[0:1], s[18:19], exec
	s_cselect_b32 s0, s3, s21
	s_or_b32 s1, s0, s86
	s_ashr_i32 s3, s0, 6
	s_bfe_u32 s15, s1, 0x50001
	s_lshl_b32 s1, s3, 10
	s_addk_i32 s1, 0x2000
	s_lshl_b32 s3, s3, 8
	s_and_b64 s[18:19], s[18:19], exec
	v_readlane_b32 s18, v253, 10
	v_readlane_b32 s19, v253, 11
	s_cselect_b32 s14, s3, s1
	s_mov_b64 s[36:37], -1
	s_and_b64 vcc, exec, s[18:19]
	s_cbranch_vccz .LBB0_578
	s_setprio 0
	s_andn2_b32 s0, s0, 63
	v_readlane_b32 s1, v253, 12
	s_or_b32 s0, s0, s1
	s_or_b32 s0, s15, s0
	s_ashr_i32 s1, s0, 31
	s_lshl_b64 s[36:37], s[0:1], 14
	v_readlane_b32 s18, v253, 0
	v_readlane_b32 s19, v253, 1
	s_load_dwordx2 s[42:43], s[18:19], 0x20
	s_load_dwordx2 s[40:41], s[18:19], 0x100
	v_mbcnt_lo_u32_b32 v195, -1, 0
	v_mbcnt_hi_u32_b32 v195, -1, v195
	v_and_b32_e32 v197, 15, v195
	v_lshrrev_b32_e32 v196, 4, v195
	v_lshlrev_b32_e32 v178, 1, v195
	v_lshlrev_b32_e32 v194, 8, v197
	v_lshl_add_u32 v194, v196, 4, v194
	v_lshlrev_b32_e32 v201, 4, v196
	v_lshlrev_b32_e32 v200, 2, v195
	v_add_u32_e32 v200, 0x2800, v200
	v_and_b32_e32 v192, 7, v195
	v_sub_u32_e32 v198, 7, v192
	v_cndmask_b32_e64 v192, v198, v192, s[12:13]
	v_lshlrev_b32_e32 v192, 8, v192
	v_mov_b32_e32 v191, v192
	v_and_b32_e32 v199, 8, v195
	v_mul_u32_u24_e32 v198, 0x300, v199
	v_add_u32_e32 v192, v192, v198
	v_add_u32_e32 v192, 0x800, v192
	v_lshlrev_b32_e32 v198, 8, v199
	v_add_u32_e32 v191, v191, v198
	v_add_u32_e32 v191, 0x1000, v191
	v_lshl_add_u32 v190, v196, 4, v192
	v_lshl_add_u32 v192, v196, 6, v192
	v_lshl_add_u32 v191, v196, 6, v191
	s_and_b64 s[0:1], s[12:13], exec
	s_movk_i32 s39, 0x100
	s_movk_i32 s74, 0x1000
	s_cselect_b32 s39, s39, 0xffffff00
	s_cselect_b32 s74, s74, 0xfffff000
	s_cselect_b32 s3, 0, -1
	s_lshl_b32 s44, s39, 1
	v_and_b32_e32 v198, 1, v196
	v_lshlrev_b32_e32 v193, 11, v198
	v_add_u32_e32 v193, 0x1000, v193
	v_lshrrev_b32_e32 v198, 1, v196
	v_mul_lo_u32 v198, v198, s39
	v_add_u32_e32 v193, v193, v198
	v_lshl_add_u32 v193, v197, 2, v193
	s_lshl_b32 s0, s86, 10
	s_add_i32 s0, s0, 0x1c010
	v_mov_b32_e32 v189, s0
	v_lshl_add_u32 v188, v197, 6, v189
	v_lshl_add_u32 v188, v196, 4, v188
	s_lshl_b32 s0, s86, 12
	s_add_i32 s0, s0, 0x20010
	v_mov_b32_e32 v199, s0
	v_lshl_add_u32 v187, v195, 6, v199
	v_lshl_add_u32 v202, v195, 2, v199
	v_lshl_add_u32 v186, v197, 6, v199
	v_lshl_add_u32 v186, v196, 4, v186
	v_lshl_add_u32 v185, v196, 8, v199
	v_lshl_add_u32 v185, v197, 2, v185
	s_waitcnt lgkmcnt(0)
	s_lshl_b32 s0, s88, 12
	s_lshl_b32 s1, s15, 7
	s_add_i32 s0, s0, s1
	s_add_u32 s100, s40, s0
	s_addc_u32 s101, s41, 0
	s_add_u32 s98, s40, 0x9200000
	s_addc_u32 s99, s41, 0
	s_add_u32 s98, s98, s36
	s_addc_u32 s99, s99, s37
	v_readlane_b32 s0, v253, 35
	v_readlane_b32 s1, v253, 36
	s_and_b64 vcc, exec, s[0:1]
	s_cbranch_vccz .Lscan_zero_state
	s_add_u32 s0, s42, s36
	s_addc_u32 s1, s43, s37
	global_load_dwordx4 v[32:35], v194, s[0:1]
	global_load_dwordx4 v[36:39], v194, s[0:1] offset:64
	global_load_dwordx4 v[40:43], v194, s[0:1] offset:128
	global_load_dwordx4 v[44:47], v194, s[0:1] offset:192
	s_add_u32 s0, s0, 0x1000
	s_addc_u32 s1, s1, 0
	global_load_dwordx4 v[48:51], v194, s[0:1]
	global_load_dwordx4 v[52:55], v194, s[0:1] offset:64
	global_load_dwordx4 v[56:59], v194, s[0:1] offset:128
	global_load_dwordx4 v[60:63], v194, s[0:1] offset:192
	s_add_u32 s0, s0, 0x1000
	s_addc_u32 s1, s1, 0
	global_load_dwordx4 v[64:67], v194, s[0:1]
	global_load_dwordx4 v[68:71], v194, s[0:1] offset:64
	global_load_dwordx4 v[72:75], v194, s[0:1] offset:128
	global_load_dwordx4 v[76:79], v194, s[0:1] offset:192
	s_add_u32 s0, s0, 0x1000
	s_addc_u32 s1, s1, 0
	global_load_dwordx4 v[80:83], v194, s[0:1]
	global_load_dwordx4 v[84:87], v194, s[0:1] offset:64
	global_load_dwordx4 v[88:91], v194, s[0:1] offset:128
	global_load_dwordx4 v[92:95], v194, s[0:1] offset:192
	s_waitcnt vmcnt(0)
	s_branch .Lscan_state_ready

.Lscan_chunk:
	s_add_i32 s0, s38, -1
	s_and_b32 s1, s0, 1
	s_lshl_b32 s1, s1, 2
	s_or_b32 s1, s1, s86
	s_mulk_i32 s1, 0x3000
	s_add_i32 s1, s1, 16
	s_add_i32 s17, s1, s59
	v_add_u32_e32 v181, s1, v191
	v_add_u32_e32 v182, s1, v192
	ds_read_b128 v[96:99], v181 offset:0
	ds_read_b128 v[100:103], v181 offset:16
	ds_read_b128 v[104:107], v181 offset:32
	ds_read_b128 v[108:111], v181 offset:48
	ds_read_b128 v[112:115], v182 offset:0
	ds_read_b128 v[116:119], v182 offset:16
	ds_read_b128 v[120:123], v182 offset:32
	ds_read_b128 v[124:127], v182 offset:48
	v_add_u32_e32 v180, s1, v190
	ds_read_b128 v[0:3], v180 offset:0
	ds_read_b128 v[4:7], v180 offset:64
	ds_read_b128 v[8:11], v180 offset:128
	ds_read_b128 v[12:15], v180 offset:192
	v_add_u32_e32 v179, s1, v201
	v_add_u32_e32 v183, s17, v193
	v_add_u32_e32 v184, s17, v200
	s_lshl_b32 s0, s0, 3
	s_sub_i32 s1, s61, s0
	s_and_b64 s[18:19], s[12:13], exec
	s_cselect_b32 s0, s0, s1
	s_add_i32 s0, s0, s14
	s_lshr_b32 s1, s59, 8
	s_add_i32 s0, s0, s1
	s_lshl_b32 s0, s0, 12
	s_add_u32 s42, s100, s0
	s_addc_u32 s43, s101, 0
	s_waitcnt lgkmcnt(4)
	v_mfma_f32_16x16x4_f32 v[128:131], v96, v112, 0
	v_mfma_f32_16x16x4_f32 v[128:131], v97, v113, v[128:131]
	v_mfma_f32_16x16x4_f32 v[128:131], v98, v114, v[128:131]
	v_mfma_f32_16x16x4_f32 v[128:131], v99, v115, v[128:131]
	v_mfma_f32_16x16x4_f32 v[128:131], v100, v116, v[128:131]
	v_mfma_f32_16x16x4_f32 v[128:131], v101, v117, v[128:131]
	v_mfma_f32_16x16x4_f32 v[128:131], v102, v118, v[128:131]
	v_mfma_f32_16x16x4_f32 v[128:131], v103, v119, v[128:131]
	v_mfma_f32_16x16x4_f32 v[128:131], v104, v120, v[128:131]
	v_mfma_f32_16x16x4_f32 v[128:131], v105, v121, v[128:131]
	v_mfma_f32_16x16x4_f32 v[128:131], v106, v122, v[128:131]
	v_mfma_f32_16x16x4_f32 v[128:131], v107, v123, v[128:131]
	v_mfma_f32_16x16x4_f32 v[128:131], v108, v124, v[128:131]
	v_mfma_f32_16x16x4_f32 v[128:131], v109, v125, v[128:131]
	v_mfma_f32_16x16x4_f32 v[128:131], v110, v126, v[128:131]
	v_mfma_f32_16x16x4_f32 v[128:131], v111, v127, v[128:131]
	ds_read_b32 v148, v183
	ds_read_b32 v149, v183 offset:64
	ds_read_b32 v150, v183 offset:128
	ds_read_b32 v151, v183 offset:192
	v_add_u32_e32 v183, s44, v183
	ds_read_b32 v152, v183
	ds_read_b32 v153, v183 offset:64
	ds_read_b32 v154, v183 offset:128
	ds_read_b32 v155, v183 offset:192
	v_add_u32_e32 v183, s44, v183
	ds_read_b32 v156, v183
	ds_read_b32 v157, v183 offset:64
	ds_read_b32 v158, v183 offset:128
	ds_read_b32 v159, v183 offset:192
	v_add_u32_e32 v183, s44, v183
	ds_read_b32 v160, v183
	ds_read_b32 v161, v183 offset:64
	ds_read_b32 v162, v183 offset:128
	ds_read_b32 v163, v183 offset:192
	ds_read_b32 v164, v184
	v_add_u32_e32 v184, s39, v184
	ds_read_b32 v165, v184
	v_add_u32_e32 v184, s39, v184
	ds_read_b32 v166, v184
	v_add_u32_e32 v184, s39, v184
	ds_read_b32 v167, v184
	v_add_u32_e32 v184, s39, v184
	ds_read_b32 v168, v184
	v_add_u32_e32 v184, s39, v184
	ds_read_b32 v169, v184
	v_add_u32_e32 v184, s39, v184
	ds_read_b32 v170, v184
	v_add_u32_e32 v184, s39, v184
	ds_read_b32 v171, v184
	s_waitcnt lgkmcnt(0)
	v_mfma_f32_16x16x4_f32 v[132:135], v0, v32, 0
	v_mfma_f32_16x16x4_f32 v[132:135], v1, v33, v[132:135]
	v_mfma_f32_16x16x4_f32 v[132:135], v2, v34, v[132:135]
	v_mfma_f32_16x16x4_f32 v[132:135], v3, v35, v[132:135]
	v_mfma_f32_16x16x4_f32 v[132:135], v4, v36, v[132:135]
	v_mfma_f32_16x16x4_f32 v[132:135], v5, v37, v[132:135]
	v_mfma_f32_16x16x4_f32 v[132:135], v6, v38, v[132:135]
	v_mfma_f32_16x16x4_f32 v[132:135], v7, v39, v[132:135]
	v_mfma_f32_16x16x4_f32 v[132:135], v8, v40, v[132:135]
	v_mfma_f32_16x16x4_f32 v[132:135], v9, v41, v[132:135]
	v_mfma_f32_16x16x4_f32 v[132:135], v10, v42, v[132:135]
	v_mfma_f32_16x16x4_f32 v[132:135], v11, v43, v[132:135]
	ds_write_b128 v188, v[128:131]
	v_mfma_f32_16x16x4_f32 v[132:135], v12, v44, v[132:135]
	v_mfma_f32_16x16x4_f32 v[132:135], v13, v45, v[132:135]
	v_mfma_f32_16x16x4_f32 v[132:135], v14, v46, v[132:135]
	v_mfma_f32_16x16x4_f32 v[132:135], v15, v47, v[132:135]
	v_mfma_f32_16x16x4_f32 v[136:139], v0, v48, 0
	v_mfma_f32_16x16x4_f32 v[136:139], v1, v49, v[136:139]
	v_mfma_f32_16x16x4_f32 v[136:139], v2, v50, v[136:139]
	v_mfma_f32_16x16x4_f32 v[136:139], v3, v51, v[136:139]
	v_mfma_f32_16x16x4_f32 v[136:139], v4, v52, v[136:139]
	v_mfma_f32_16x16x4_f32 v[136:139], v5, v53, v[136:139]
	v_mfma_f32_16x16x4_f32 v[136:139], v6, v54, v[136:139]
	v_mfma_f32_16x16x4_f32 v[136:139], v7, v55, v[136:139]
	v_mfma_f32_16x16x4_f32 v[136:139], v8, v56, v[136:139]
	v_mfma_f32_16x16x4_f32 v[136:139], v9, v57, v[136:139]
	v_mfma_f32_16x16x4_f32 v[136:139], v10, v58, v[136:139]
	v_mfma_f32_16x16x4_f32 v[136:139], v11, v59, v[136:139]
	v_mfma_f32_16x16x4_f32 v[136:139], v12, v60, v[136:139]
	v_mfma_f32_16x16x4_f32 v[136:139], v13, v61, v[136:139]
	v_mfma_f32_16x16x4_f32 v[136:139], v14, v62, v[136:139]
	v_mfma_f32_16x16x4_f32 v[136:139], v15, v63, v[136:139]
	ds_write_b128 v186, v[132:135]
	v_mfma_f32_16x16x4_f32 v[140:143], v0, v64, 0
	v_mfma_f32_16x16x4_f32 v[140:143], v1, v65, v[140:143]
	v_mfma_f32_16x16x4_f32 v[140:143], v2, v66, v[140:143]
	v_mfma_f32_16x16x4_f32 v[140:143], v3, v67, v[140:143]
	v_mfma_f32_16x16x4_f32 v[140:143], v4, v68, v[140:143]
	v_mfma_f32_16x16x4_f32 v[140:143], v5, v69, v[140:143]
	v_mfma_f32_16x16x4_f32 v[140:143], v6, v70, v[140:143]
	v_mfma_f32_16x16x4_f32 v[140:143], v7, v71, v[140:143]
	v_mfma_f32_16x16x4_f32 v[140:143], v8, v72, v[140:143]
	v_mfma_f32_16x16x4_f32 v[140:143], v9, v73, v[140:143]
	v_mfma_f32_16x16x4_f32 v[140:143], v10, v74, v[140:143]
	v_mfma_f32_16x16x4_f32 v[140:143], v11, v75, v[140:143]
	v_mfma_f32_16x16x4_f32 v[140:143], v12, v76, v[140:143]
	v_mfma_f32_16x16x4_f32 v[140:143], v13, v77, v[140:143]
	v_mfma_f32_16x16x4_f32 v[140:143], v14, v78, v[140:143]
	v_mfma_f32_16x16x4_f32 v[140:143], v15, v79, v[140:143]
	ds_write_b128 v186, v[136:139] offset:1024
	v_mfma_f32_16x16x4_f32 v[144:147], v0, v80, 0
	v_mfma_f32_16x16x4_f32 v[144:147], v1, v81, v[144:147]
	v_mfma_f32_16x16x4_f32 v[144:147], v2, v82, v[144:147]
	v_mfma_f32_16x16x4_f32 v[144:147], v3, v83, v[144:147]
	v_mfma_f32_16x16x4_f32 v[144:147], v4, v84, v[144:147]
	v_mfma_f32_16x16x4_f32 v[144:147], v5, v85, v[144:147]
	v_mfma_f32_16x16x4_f32 v[144:147], v6, v86, v[144:147]
	v_mfma_f32_16x16x4_f32 v[144:147], v7, v87, v[144:147]
	v_mfma_f32_16x16x4_f32 v[144:147], v8, v88, v[144:147]
	v_mfma_f32_16x16x4_f32 v[144:147], v9, v89, v[144:147]
	v_mfma_f32_16x16x4_f32 v[144:147], v10, v90, v[144:147]
	v_mfma_f32_16x16x4_f32 v[144:147], v11, v91, v[144:147]
	v_mfma_f32_16x16x4_f32 v[144:147], v12, v92, v[144:147]
	v_mfma_f32_16x16x4_f32 v[144:147], v13, v93, v[144:147]
	v_mfma_f32_16x16x4_f32 v[144:147], v14, v94, v[144:147]
	v_mfma_f32_16x16x4_f32 v[144:147], v15, v95, v[144:147]
	ds_write_b128 v186, v[140:143] offset:2048
	s_nop 7
	s_nop 3
	ds_write_b128 v186, v[144:147] offset:3072
	ds_read_b128 v[0:3], v179 offset:0
	ds_read_b128 v[4:7], v179 offset:64
	ds_read_b128 v[8:11], v179 offset:128
	ds_read_b128 v[12:15], v179 offset:192
	s_waitcnt lgkmcnt(4)
	ds_read_b128 v[220:223], v187 offset:0
	ds_read_b128 v[224:227], v187 offset:16
	ds_read_b128 v[228:231], v187 offset:32
	ds_read_b128 v[232:235], v187 offset:48
	ds_read_b128 v[16:19], v189 offset:0
	ds_read_b128 v[20:23], v189 offset:16
	ds_read_b128 v[24:27], v189 offset:32
	ds_read_b128 v[28:31], v189 offset:48
	ds_read_b128 v[236:239], v189 offset:512
	ds_read_b128 v[240:243], v189 offset:528
	ds_read_b128 v[244:247], v189 offset:544
	ds_read_b128 v[248:251], v189 offset:560
	s_waitcnt lgkmcnt(0)
	ds_read_b128 v[96:99], v189 offset:64
	ds_read_b128 v[100:103], v189 offset:80
	ds_read_b128 v[104:107], v189 offset:96
	ds_read_b128 v[108:111], v189 offset:112
	ds_read_b128 v[112:115], v189 offset:576
	ds_read_b128 v[116:119], v189 offset:592
	ds_read_b128 v[120:123], v189 offset:608
	ds_read_b128 v[124:127], v189 offset:624
	v_sub_f32_e32 v176, 0, v220
	v_fma_f32 v228, -v220, v236, v228
	v_fmac_f32_e32 v228, v164, v244
	ds_write_b32 v202, v176 offset:0
	ds_write_b32 v202, v164 offset:256
	v_cvt_pk_bf16_f32 v177, v228, v228
	global_store_short v178, v177, s[42:43]
	s_add_u32 s42, s42, s74
	s_addc_u32 s43, s43, s3
	s_waitcnt lgkmcnt(0)
	ds_read_b128 v[16:19], v189 offset:128
	ds_read_b128 v[20:23], v189 offset:144
	ds_read_b128 v[24:27], v189 offset:160
	ds_read_b128 v[28:31], v189 offset:176
	ds_read_b128 v[236:239], v189 offset:640
	ds_read_b128 v[240:243], v189 offset:656
	ds_read_b128 v[244:247], v189 offset:672
	ds_read_b128 v[248:251], v189 offset:688
	v_fma_f32 v221, -v220, v96, v221
	v_fmac_f32_e32 v221, v164, v104
	v_sub_f32_e32 v176, 0, v221
	v_fma_f32 v229, -v220, v112, v229
	v_fmac_f32_e32 v229, v164, v120
	v_fma_f32 v229, -v221, v113, v229
	v_fmac_f32_e32 v229, v165, v121
	ds_write_b32 v202, v176 offset:512
	ds_write_b32 v202, v165 offset:768
	v_cvt_pk_bf16_f32 v177, v229, v229
	global_store_short v178, v177, s[42:43]
	s_add_u32 s42, s42, s74
	s_addc_u32 s43, s43, s3
	ds_read_b32 v172, v185 offset:0
	ds_read_b32 v173, v185 offset:64
	ds_read_b32 v174, v185 offset:128
	ds_read_b32 v175, v185 offset:192
	s_waitcnt lgkmcnt(0)
	v_mfma_f32_16x16x4_f32 v[32:35], v148, v172, v[32:35]
	v_mfma_f32_16x16x4_f32 v[36:39], v149, v172, v[36:39]
	v_mfma_f32_16x16x4_f32 v[40:43], v150, v172, v[40:43]
	v_mfma_f32_16x16x4_f32 v[44:47], v151, v172, v[44:47]
	v_mfma_f32_16x16x4_f32 v[48:51], v148, v173, v[48:51]
	v_mfma_f32_16x16x4_f32 v[52:55], v149, v173, v[52:55]
	v_mfma_f32_16x16x4_f32 v[56:59], v150, v173, v[56:59]
	v_mfma_f32_16x16x4_f32 v[60:63], v151, v173, v[60:63]
	v_mfma_f32_16x16x4_f32 v[64:67], v148, v174, v[64:67]
	v_mfma_f32_16x16x4_f32 v[68:71], v149, v174, v[68:71]
	v_mfma_f32_16x16x4_f32 v[72:75], v150, v174, v[72:75]
	v_mfma_f32_16x16x4_f32 v[76:79], v151, v174, v[76:79]
	v_mfma_f32_16x16x4_f32 v[80:83], v148, v175, v[80:83]
	v_mfma_f32_16x16x4_f32 v[84:87], v149, v175, v[84:87]
	v_mfma_f32_16x16x4_f32 v[88:91], v150, v175, v[88:91]
	v_mfma_f32_16x16x4_f32 v[92:95], v151, v175, v[92:95]
	s_waitcnt lgkmcnt(0)
	ds_read_b128 v[96:99], v189 offset:192
	ds_read_b128 v[100:103], v189 offset:208
	ds_read_b128 v[104:107], v189 offset:224
	ds_read_b128 v[108:111], v189 offset:240
	ds_read_b128 v[112:115], v189 offset:704
	ds_read_b128 v[116:119], v189 offset:720
	ds_read_b128 v[120:123], v189 offset:736
	ds_read_b128 v[124:127], v189 offset:752
	v_fma_f32 v222, -v220, v16, v222
	v_fmac_f32_e32 v222, v164, v24
	v_fma_f32 v222, -v221, v17, v222
	v_fmac_f32_e32 v222, v165, v25
	v_sub_f32_e32 v176, 0, v222
	v_fma_f32 v230, -v220, v236, v230
	v_fmac_f32_e32 v230, v164, v244
	v_fma_f32 v230, -v221, v237, v230
	v_fmac_f32_e32 v230, v165, v245
	v_fma_f32 v230, -v222, v238, v230
	v_fmac_f32_e32 v230, v166, v246
	ds_write_b32 v202, v176 offset:1024
	ds_write_b32 v202, v166 offset:1280
	v_cvt_pk_bf16_f32 v177, v230, v230
	global_store_short v178, v177, s[42:43]
	s_add_u32 s42, s42, s74
	s_addc_u32 s43, s43, s3
	s_waitcnt lgkmcnt(0)
	ds_read_b128 v[16:19], v189 offset:256
	ds_read_b128 v[20:23], v189 offset:272
	ds_read_b128 v[24:27], v189 offset:288
	ds_read_b128 v[28:31], v189 offset:304
	ds_read_b128 v[236:239], v189 offset:768
	ds_read_b128 v[240:243], v189 offset:784
	ds_read_b128 v[244:247], v189 offset:800
	ds_read_b128 v[248:251], v189 offset:816
	v_fma_f32 v223, -v220, v96, v223
	v_fmac_f32_e32 v223, v164, v104
	v_fma_f32 v223, -v221, v97, v223
	v_fmac_f32_e32 v223, v165, v105
	v_fma_f32 v223, -v222, v98, v223
	v_fmac_f32_e32 v223, v166, v106
	v_sub_f32_e32 v176, 0, v223
	v_fma_f32 v231, -v220, v112, v231
	v_fmac_f32_e32 v231, v164, v120
	v_fma_f32 v231, -v221, v113, v231
	v_fmac_f32_e32 v231, v165, v121
	v_fma_f32 v231, -v222, v114, v231
	v_fmac_f32_e32 v231, v166, v122
	v_fma_f32 v231, -v223, v115, v231
	v_fmac_f32_e32 v231, v167, v123
	ds_write_b32 v202, v176 offset:1536
	ds_write_b32 v202, v167 offset:1792
	v_cvt_pk_bf16_f32 v177, v231, v231
	global_store_short v178, v177, s[42:43]
	s_add_u32 s42, s42, s74
	s_addc_u32 s43, s43, s3
	ds_read_b32 v172, v185 offset:1024
	ds_read_b32 v173, v185 offset:1088
	ds_read_b32 v174, v185 offset:1152
	ds_read_b32 v175, v185 offset:1216
	s_waitcnt lgkmcnt(0)
	v_mfma_f32_16x16x4_f32 v[32:35], v152, v172, v[32:35]
	v_mfma_f32_16x16x4_f32 v[36:39], v153, v172, v[36:39]
	v_mfma_f32_16x16x4_f32 v[40:43], v154, v172, v[40:43]
	v_mfma_f32_16x16x4_f32 v[44:47], v155, v172, v[44:47]
	v_mfma_f32_16x16x4_f32 v[48:51], v152, v173, v[48:51]
	v_mfma_f32_16x16x4_f32 v[52:55], v153, v173, v[52:55]
	v_mfma_f32_16x16x4_f32 v[56:59], v154, v173, v[56:59]
	v_mfma_f32_16x16x4_f32 v[60:63], v155, v173, v[60:63]
	v_mfma_f32_16x16x4_f32 v[64:67], v152, v174, v[64:67]
	v_mfma_f32_16x16x4_f32 v[68:71], v153, v174, v[68:71]
	v_mfma_f32_16x16x4_f32 v[72:75], v154, v174, v[72:75]
	v_mfma_f32_16x16x4_f32 v[76:79], v155, v174, v[76:79]
	v_mfma_f32_16x16x4_f32 v[80:83], v152, v175, v[80:83]
	v_mfma_f32_16x16x4_f32 v[84:87], v153, v175, v[84:87]
	v_mfma_f32_16x16x4_f32 v[88:91], v154, v175, v[88:91]
	v_mfma_f32_16x16x4_f32 v[92:95], v155, v175, v[92:95]
	s_waitcnt lgkmcnt(0)
	ds_read_b128 v[96:99], v189 offset:320
	ds_read_b128 v[100:103], v189 offset:336
	ds_read_b128 v[104:107], v189 offset:352
	ds_read_b128 v[108:111], v189 offset:368
	ds_read_b128 v[112:115], v189 offset:832
	ds_read_b128 v[116:119], v189 offset:848
	ds_read_b128 v[120:123], v189 offset:864
	ds_read_b128 v[124:127], v189 offset:880
	v_fma_f32 v224, -v220, v16, v224
	v_fmac_f32_e32 v224, v164, v24
	v_fma_f32 v224, -v221, v17, v224
	v_fmac_f32_e32 v224, v165, v25
	v_fma_f32 v224, -v222, v18, v224
	v_fmac_f32_e32 v224, v166, v26
	v_fma_f32 v224, -v223, v19, v224
	v_fmac_f32_e32 v224, v167, v27
	v_sub_f32_e32 v176, 0, v224
	v_fma_f32 v232, -v220, v236, v232
	v_fmac_f32_e32 v232, v164, v244
	v_fma_f32 v232, -v221, v237, v232
	v_fmac_f32_e32 v232, v165, v245
	v_fma_f32 v232, -v222, v238, v232
	v_fmac_f32_e32 v232, v166, v246
	v_fma_f32 v232, -v223, v239, v232
	v_fmac_f32_e32 v232, v167, v247
	v_fma_f32 v232, -v224, v240, v232
	v_fmac_f32_e32 v232, v168, v248
	ds_write_b32 v202, v176 offset:2048
	ds_write_b32 v202, v168 offset:2304
	v_cvt_pk_bf16_f32 v177, v232, v232
	global_store_short v178, v177, s[42:43]
	s_add_u32 s42, s42, s74
	s_addc_u32 s43, s43, s3
	s_waitcnt lgkmcnt(0)
	ds_read_b128 v[16:19], v189 offset:384
	ds_read_b128 v[20:23], v189 offset:400
	ds_read_b128 v[24:27], v189 offset:416
	ds_read_b128 v[28:31], v189 offset:432
	ds_read_b128 v[236:239], v189 offset:896
	ds_read_b128 v[240:243], v189 offset:912
	ds_read_b128 v[244:247], v189 offset:928
	ds_read_b128 v[248:251], v189 offset:944
	v_fma_f32 v225, -v220, v96, v225
	v_fmac_f32_e32 v225, v164, v104
	v_fma_f32 v225, -v221, v97, v225
	v_fmac_f32_e32 v225, v165, v105
	v_fma_f32 v225, -v222, v98, v225
	v_fmac_f32_e32 v225, v166, v106
	v_fma_f32 v225, -v223, v99, v225
	v_fmac_f32_e32 v225, v167, v107
	v_fma_f32 v225, -v224, v100, v225
	v_fmac_f32_e32 v225, v168, v108
	v_sub_f32_e32 v176, 0, v225
	v_fma_f32 v233, -v220, v112, v233
	v_fmac_f32_e32 v233, v164, v120
	v_fma_f32 v233, -v221, v113, v233
	v_fmac_f32_e32 v233, v165, v121
	v_fma_f32 v233, -v222, v114, v233
	v_fmac_f32_e32 v233, v166, v122
	v_fma_f32 v233, -v223, v115, v233
	v_fmac_f32_e32 v233, v167, v123
	v_fma_f32 v233, -v224, v116, v233
	v_fmac_f32_e32 v233, v168, v124
	v_fma_f32 v233, -v225, v117, v233
	v_fmac_f32_e32 v233, v169, v125
	ds_write_b32 v202, v176 offset:2560
	ds_write_b32 v202, v169 offset:2816
	v_cvt_pk_bf16_f32 v177, v233, v233
	global_store_short v178, v177, s[42:43]
	s_add_u32 s42, s42, s74
	s_addc_u32 s43, s43, s3
	ds_read_b32 v172, v185 offset:2048
	ds_read_b32 v173, v185 offset:2112
	ds_read_b32 v174, v185 offset:2176
	ds_read_b32 v175, v185 offset:2240
	s_waitcnt lgkmcnt(0)
	v_mfma_f32_16x16x4_f32 v[32:35], v156, v172, v[32:35]
	v_mfma_f32_16x16x4_f32 v[36:39], v157, v172, v[36:39]
	v_mfma_f32_16x16x4_f32 v[40:43], v158, v172, v[40:43]
	v_mfma_f32_16x16x4_f32 v[44:47], v159, v172, v[44:47]
	v_mfma_f32_16x16x4_f32 v[48:51], v156, v173, v[48:51]
	v_mfma_f32_16x16x4_f32 v[52:55], v157, v173, v[52:55]
	v_mfma_f32_16x16x4_f32 v[56:59], v158, v173, v[56:59]
	v_mfma_f32_16x16x4_f32 v[60:63], v159, v173, v[60:63]
	v_mfma_f32_16x16x4_f32 v[64:67], v156, v174, v[64:67]
	v_mfma_f32_16x16x4_f32 v[68:71], v157, v174, v[68:71]
	v_mfma_f32_16x16x4_f32 v[72:75], v158, v174, v[72:75]
	v_mfma_f32_16x16x4_f32 v[76:79], v159, v174, v[76:79]
	v_mfma_f32_16x16x4_f32 v[80:83], v156, v175, v[80:83]
	v_mfma_f32_16x16x4_f32 v[84:87], v157, v175, v[84:87]
	v_mfma_f32_16x16x4_f32 v[88:91], v158, v175, v[88:91]
	v_mfma_f32_16x16x4_f32 v[92:95], v159, v175, v[92:95]
	s_waitcnt lgkmcnt(0)
	ds_read_b128 v[96:99], v189 offset:448
	ds_read_b128 v[100:103], v189 offset:464
	ds_read_b128 v[104:107], v189 offset:480
	ds_read_b128 v[108:111], v189 offset:496
	ds_read_b128 v[112:115], v189 offset:960
	ds_read_b128 v[116:119], v189 offset:976
	ds_read_b128 v[120:123], v189 offset:992
	ds_read_b128 v[124:127], v189 offset:1008
	v_fma_f32 v226, -v220, v16, v226
	v_fmac_f32_e32 v226, v164, v24
	v_fma_f32 v226, -v221, v17, v226
	v_fmac_f32_e32 v226, v165, v25
	v_fma_f32 v226, -v222, v18, v226
	v_fmac_f32_e32 v226, v166, v26
	v_fma_f32 v226, -v223, v19, v226
	v_fmac_f32_e32 v226, v167, v27
	v_fma_f32 v226, -v224, v20, v226
	v_fmac_f32_e32 v226, v168, v28
	v_fma_f32 v226, -v225, v21, v226
	v_fmac_f32_e32 v226, v169, v29
	v_sub_f32_e32 v176, 0, v226
	v_fma_f32 v234, -v220, v236, v234
	v_fmac_f32_e32 v234, v164, v244
	v_fma_f32 v234, -v221, v237, v234
	v_fmac_f32_e32 v234, v165, v245
	v_fma_f32 v234, -v222, v238, v234
	v_fmac_f32_e32 v234, v166, v246
	v_fma_f32 v234, -v223, v239, v234
	v_fmac_f32_e32 v234, v167, v247
	v_fma_f32 v234, -v224, v240, v234
	v_fmac_f32_e32 v234, v168, v248
	v_fma_f32 v234, -v225, v241, v234
	v_fmac_f32_e32 v234, v169, v249
	v_fma_f32 v234, -v226, v242, v234
	v_fmac_f32_e32 v234, v170, v250
	ds_write_b32 v202, v176 offset:3072
	ds_write_b32 v202, v170 offset:3328
	v_cvt_pk_bf16_f32 v177, v234, v234
	global_store_short v178, v177, s[42:43]
	s_add_u32 s42, s42, s74
	s_addc_u32 s43, s43, s3
	s_waitcnt lgkmcnt(0)
	v_fma_f32 v227, -v220, v96, v227
	v_fmac_f32_e32 v227, v164, v104
	v_fma_f32 v227, -v221, v97, v227
	v_fmac_f32_e32 v227, v165, v105
	v_fma_f32 v227, -v222, v98, v227
	v_fmac_f32_e32 v227, v166, v106
	v_fma_f32 v227, -v223, v99, v227
	v_fmac_f32_e32 v227, v167, v107
	v_fma_f32 v227, -v224, v100, v227
	v_fmac_f32_e32 v227, v168, v108
	v_fma_f32 v227, -v225, v101, v227
	v_fmac_f32_e32 v227, v169, v109
	v_fma_f32 v227, -v226, v102, v227
	v_fmac_f32_e32 v227, v170, v110
	v_sub_f32_e32 v176, 0, v227
	v_fma_f32 v235, -v220, v112, v235
	v_fmac_f32_e32 v235, v164, v120
	v_fma_f32 v235, -v221, v113, v235
	v_fmac_f32_e32 v235, v165, v121
	v_fma_f32 v235, -v222, v114, v235
	v_fmac_f32_e32 v235, v166, v122
	v_fma_f32 v235, -v223, v115, v235
	v_fmac_f32_e32 v235, v167, v123
	v_fma_f32 v235, -v224, v116, v235
	v_fmac_f32_e32 v235, v168, v124
	v_fma_f32 v235, -v225, v117, v235
	v_fmac_f32_e32 v235, v169, v125
	v_fma_f32 v235, -v226, v118, v235
	v_fmac_f32_e32 v235, v170, v126
	v_fma_f32 v235, -v227, v119, v235
	v_fmac_f32_e32 v235, v171, v127
	ds_write_b32 v202, v176 offset:3584
	ds_write_b32 v202, v171 offset:3840
	v_cvt_pk_bf16_f32 v177, v235, v235
	global_store_short v178, v177, s[42:43]
	s_add_u32 s42, s42, s74
	s_addc_u32 s43, s43, s3
	ds_read_b32 v172, v185 offset:3072
	ds_read_b32 v173, v185 offset:3136
	ds_read_b32 v174, v185 offset:3200
	ds_read_b32 v175, v185 offset:3264
	s_waitcnt lgkmcnt(0)
	v_mfma_f32_16x16x4_f32 v[32:35], v160, v172, v[32:35]
	v_mfma_f32_16x16x4_f32 v[36:39], v161, v172, v[36:39]
	v_mfma_f32_16x16x4_f32 v[40:43], v162, v172, v[40:43]
	v_mfma_f32_16x16x4_f32 v[44:47], v163, v172, v[44:47]
	v_mfma_f32_16x16x4_f32 v[48:51], v160, v173, v[48:51]
	v_mfma_f32_16x16x4_f32 v[52:55], v161, v173, v[52:55]
	v_mfma_f32_16x16x4_f32 v[56:59], v162, v173, v[56:59]
	v_mfma_f32_16x16x4_f32 v[60:63], v163, v173, v[60:63]
	v_mfma_f32_16x16x4_f32 v[64:67], v160, v174, v[64:67]
	v_mfma_f32_16x16x4_f32 v[68:71], v161, v174, v[68:71]
	v_mfma_f32_16x16x4_f32 v[72:75], v162, v174, v[72:75]
	v_mfma_f32_16x16x4_f32 v[76:79], v163, v174, v[76:79]
	v_mfma_f32_16x16x4_f32 v[80:83], v160, v175, v[80:83]
	v_mfma_f32_16x16x4_f32 v[84:87], v161, v175, v[84:87]
	v_mfma_f32_16x16x4_f32 v[88:91], v162, v175, v[88:91]
	v_mfma_f32_16x16x4_f32 v[92:95], v163, v175, v[92:95]
	s_nop 7
	s_nop 3
	v_pk_mul_f32 v[32:33], v[32:33], v[0:1]
	v_pk_mul_f32 v[34:35], v[34:35], v[2:3]
	v_pk_mul_f32 v[36:37], v[36:37], v[4:5]
	v_pk_mul_f32 v[38:39], v[38:39], v[6:7]
	v_pk_mul_f32 v[40:41], v[40:41], v[8:9]
	v_pk_mul_f32 v[42:43], v[42:43], v[10:11]
	v_pk_mul_f32 v[44:45], v[44:45], v[12:13]
	v_pk_mul_f32 v[46:47], v[46:47], v[14:15]
	v_pk_mul_f32 v[48:49], v[48:49], v[0:1]
	v_pk_mul_f32 v[50:51], v[50:51], v[2:3]
	v_pk_mul_f32 v[52:53], v[52:53], v[4:5]
	v_pk_mul_f32 v[54:55], v[54:55], v[6:7]
	v_pk_mul_f32 v[56:57], v[56:57], v[8:9]
	v_pk_mul_f32 v[58:59], v[58:59], v[10:11]
	v_pk_mul_f32 v[60:61], v[60:61], v[12:13]
	v_pk_mul_f32 v[62:63], v[62:63], v[14:15]
	v_pk_mul_f32 v[64:65], v[64:65], v[0:1]
	v_pk_mul_f32 v[66:67], v[66:67], v[2:3]
	v_pk_mul_f32 v[68:69], v[68:69], v[4:5]
	v_pk_mul_f32 v[70:71], v[70:71], v[6:7]
	v_pk_mul_f32 v[72:73], v[72:73], v[8:9]
	v_pk_mul_f32 v[74:75], v[74:75], v[10:11]
	v_pk_mul_f32 v[76:77], v[76:77], v[12:13]
	v_pk_mul_f32 v[78:79], v[78:79], v[14:15]
	v_pk_mul_f32 v[80:81], v[80:81], v[0:1]
	v_pk_mul_f32 v[82:83], v[82:83], v[2:3]
	v_pk_mul_f32 v[84:85], v[84:85], v[4:5]
	v_pk_mul_f32 v[86:87], v[86:87], v[6:7]
	v_pk_mul_f32 v[88:89], v[88:89], v[8:9]
	v_pk_mul_f32 v[90:91], v[90:91], v[10:11]
	v_pk_mul_f32 v[92:93], v[92:93], v[12:13]
	v_pk_mul_f32 v[94:95], v[94:95], v[14:15]

.Lscan_done:
	v_readlane_b32 s0, v253, 37
	v_readlane_b32 s1, v253, 38
	s_and_b64 vcc, exec, s[0:1]
	s_cbranch_vccz .LBB0_577
	s_mov_b32 s0, s98
	s_mov_b32 s1, s99
	global_store_dwordx4 v194, v[32:35], s[0:1]
	global_store_dwordx4 v194, v[36:39], s[0:1] offset:64
	global_store_dwordx4 v194, v[40:43], s[0:1] offset:128
	global_store_dwordx4 v194, v[44:47], s[0:1] offset:192
	s_add_u32 s0, s0, 0x1000
	s_addc_u32 s1, s1, 0
	global_store_dwordx4 v194, v[48:51], s[0:1]
	global_store_dwordx4 v194, v[52:55], s[0:1] offset:64
	global_store_dwordx4 v194, v[56:59], s[0:1] offset:128
	global_store_dwordx4 v194, v[60:63], s[0:1] offset:192
	s_add_u32 s0, s0, 0x1000
	s_addc_u32 s1, s1, 0
	global_store_dwordx4 v194, v[64:67], s[0:1]
	global_store_dwordx4 v194, v[68:71], s[0:1] offset:64
	global_store_dwordx4 v194, v[72:75], s[0:1] offset:128
	global_store_dwordx4 v194, v[76:79], s[0:1] offset:192
	s_add_u32 s0, s0, 0x1000
	s_addc_u32 s1, s1, 0
	global_store_dwordx4 v194, v[80:83], s[0:1]
	global_store_dwordx4 v194, v[84:87], s[0:1] offset:64
	global_store_dwordx4 v194, v[88:91], s[0:1] offset:128
	global_store_dwordx4 v194, v[92:95], s[0:1] offset:192

	.amdhsa_kernel _Z14fwd_megakernel6Paramsii
		.amdhsa_group_segment_fixed_size 16400
		.amdhsa_private_segment_fixed_size 0
		.amdhsa_kernarg_size 536
		.amdhsa_user_sgpr_count 2
		.amdhsa_user_sgpr_dispatch_ptr 0
		.amdhsa_user_sgpr_queue_ptr 0
		.amdhsa_user_sgpr_kernarg_segment_ptr 1
		.amdhsa_user_sgpr_dispatch_id 0
		.amdhsa_user_sgpr_kernarg_preload_length 0
		.amdhsa_user_sgpr_kernarg_preload_offset 0
		.amdhsa_user_sgpr_private_segment_size 0
		.amdhsa_uses_dynamic_stack 0
		.amdhsa_enable_private_segment 0
		.amdhsa_system_sgpr_workgroup_id_x 1
		.amdhsa_system_sgpr_workgroup_id_y 0
		.amdhsa_system_sgpr_workgroup_id_z 0
		.amdhsa_system_sgpr_workgroup_info 0
		.amdhsa_system_vgpr_workitem_id 2
		.amdhsa_next_free_vgpr 254
		.amdhsa_next_free_sgpr 102
		.amdhsa_accum_offset 256
		.amdhsa_reserve_vcc 1
		.amdhsa_float_round_mode_32 0
		.amdhsa_float_round_mode_16_64 0
		.amdhsa_float_denorm_mode_32 3
		.amdhsa_float_denorm_mode_16_64 3
		.amdhsa_dx10_clamp 1
		.amdhsa_ieee_mode 1
		.amdhsa_fp16_overflow 0
		.amdhsa_tg_split 0
		.amdhsa_exception_fp_ieee_invalid_op 0
		.amdhsa_exception_fp_denorm_src 0
		.amdhsa_exception_fp_ieee_div_zero 0
		.amdhsa_exception_fp_ieee_overflow 0
		.amdhsa_exception_fp_ieee_underflow 0
		.amdhsa_exception_fp_ieee_inexact 0
		.amdhsa_exception_int_div_zero 0
	.end_amdhsa_kernel

amdhsa.kernels:
  - .agpr_count:     0
    .args:
      - .offset:         0
        .size:           272
        .value_kind:     by_value
      - .offset:         272
        .size:           4
        .value_kind:     by_value
      - .offset:         276
        .size:           4
        .value_kind:     by_value
      - .offset:         280
        .size:           4
        .value_kind:     hidden_block_count_x
      - .offset:         284
        .size:           4
        .value_kind:     hidden_block_count_y
      - .offset:         288
        .size:           4
        .value_kind:     hidden_block_count_z
      - .offset:         292
        .size:           2
        .value_kind:     hidden_group_size_x
      - .offset:         294
        .size:           2
        .value_kind:     hidden_group_size_y
      - .offset:         296
        .size:           2
        .value_kind:     hidden_group_size_z
      - .offset:         298
        .size:           2
        .value_kind:     hidden_remainder_x
      - .offset:         300
        .size:           2
        .value_kind:     hidden_remainder_y
      - .offset:         302
        .size:           2
        .value_kind:     hidden_remainder_z
      - .offset:         320
        .size:           8
        .value_kind:     hidden_global_offset_x
      - .offset:         328
        .size:           8
        .value_kind:     hidden_global_offset_y
      - .offset:         336
        .size:           8
        .value_kind:     hidden_global_offset_z
      - .offset:         344
        .size:           2
        .value_kind:     hidden_grid_dims
      - .offset:         368
        .size:           8
        .value_kind:     hidden_multigrid_sync_arg
      - .offset:         400
        .size:           4
        .value_kind:     hidden_dynamic_lds_size
    .group_segment_fixed_size: 16400
    .kernarg_segment_align: 8
    .kernarg_segment_size: 536
    .language:       OpenCL C
    .language_version:
      - 2
      - 0
    .max_flat_workgroup_size: 512
    .name:           _Z14fwd_megakernel6Paramsii
    .private_segment_fixed_size: 0
    .sgpr_count:     108
    .sgpr_spill_count: 73
    .symbol:         _Z14fwd_megakernel6Paramsii.kd
    .uniform_work_group_size: 1
    .uses_dynamic_stack: false
    .vgpr_count:     254
    .vgpr_spill_count: 0
    .wavefront_size: 64
